# E23: pool unit X-row staging unrolled (5 loads in flight, one wait) for prompt units; on E21
# speedup vs baseline: 1.0085x; 1.0085x over previous
.LBB0_425:
	s_lshl_b32 s6, s51, 4
	v_lshl_add_u32 v10, s18, 6, v217
	s_or_b32 s46, s6, 0xf0
	s_and_b32 s58, s96, 3
	v_cmp_gt_i32_e32 vcc, s46, v10
	s_and_saveexec_b64 s[6:7], vcc
	s_cbranch_execz .LBB0_448
	s_lshl_b32 s18, s58, 8
	v_lshl_add_u64 v[12:13], v[160:161], 0, s[18:19]
	s_lshl_b32 s18, s58, 9
	s_add_i32 s47, s49, -15
	s_add_i32 s59, s50, -15
	v_lshl_add_u64 v[14:15], v[156:157], 0, s[18:19]
	s_mov_b64 s[42:43], 0
	v_mov_b32_e32 v11, v10
	s_andn2_b64 vcc, exec, s[40:41]
	s_cbranch_vccnz .LBB0_429
	v_ashrrev_i32_e32 v66, 4, v10
	v_mad_u32_u24 v88, v66, s3, v152
	v_add_u32_e32 v66, s47, v66
	v_cmp_lt_i32_e32 vcc, -1, v66
	v_mov_b32_e32 v68, 0
	v_mov_b32_e32 v69, 0
	v_mov_b32_e32 v70, 0
	v_mov_b32_e32 v71, 0
	v_mov_b32_e32 v67, 0
	s_and_saveexec_b64 s[44:45], vcc
	v_add_u32_e32 v66, s50, v66
	v_lshlrev_b64 v[66:67], 10, v[66:67]
	v_lshl_add_u64 v[66:67], v[12:13], 0, v[66:67]
	global_load_dwordx4 v[68:71], v[66:67], off
	s_or_b64 exec, exec, s[44:45]
	v_add_u32_e32 v65, 0x200, v10
	v_ashrrev_i32_e32 v66, 4, v65
	v_mad_u32_u24 v89, v66, s3, v152
	v_add_u32_e32 v66, s47, v66
	v_cmp_lt_i32_e32 vcc, -1, v66
	v_mov_b32_e32 v72, 0
	v_mov_b32_e32 v73, 0
	v_mov_b32_e32 v74, 0
	v_mov_b32_e32 v75, 0
	v_mov_b32_e32 v67, 0
	s_and_saveexec_b64 s[44:45], vcc
	v_add_u32_e32 v66, s50, v66
	v_lshlrev_b64 v[66:67], 10, v[66:67]
	v_lshl_add_u64 v[66:67], v[12:13], 0, v[66:67]
	global_load_dwordx4 v[72:75], v[66:67], off
	s_or_b64 exec, exec, s[44:45]
	v_add_u32_e32 v65, 0x400, v10
	v_ashrrev_i32_e32 v66, 4, v65
	v_mad_u32_u24 v90, v66, s3, v152
	v_add_u32_e32 v66, s47, v66
	v_cmp_lt_i32_e32 vcc, -1, v66
	v_mov_b32_e32 v76, 0
	v_mov_b32_e32 v77, 0
	v_mov_b32_e32 v78, 0
	v_mov_b32_e32 v79, 0
	v_mov_b32_e32 v67, 0
	s_and_saveexec_b64 s[44:45], vcc
	v_add_u32_e32 v66, s50, v66
	v_lshlrev_b64 v[66:67], 10, v[66:67]
	v_lshl_add_u64 v[66:67], v[12:13], 0, v[66:67]
	global_load_dwordx4 v[76:79], v[66:67], off
	s_or_b64 exec, exec, s[44:45]
	v_add_u32_e32 v65, 0x600, v10
	v_ashrrev_i32_e32 v66, 4, v65
	v_mad_u32_u24 v91, v66, s3, v152
	v_add_u32_e32 v66, s47, v66
	v_cmp_lt_i32_e32 vcc, -1, v66
	v_mov_b32_e32 v80, 0
	v_mov_b32_e32 v81, 0
	v_mov_b32_e32 v82, 0
	v_mov_b32_e32 v83, 0
	v_mov_b32_e32 v67, 0
	s_and_saveexec_b64 s[44:45], vcc
	v_add_u32_e32 v66, s50, v66
	v_lshlrev_b64 v[66:67], 10, v[66:67]
	v_lshl_add_u64 v[66:67], v[12:13], 0, v[66:67]
	global_load_dwordx4 v[80:83], v[66:67], off
	s_or_b64 exec, exec, s[44:45]
	v_add_u32_e32 v65, 0x800, v10
	v_ashrrev_i32_e32 v66, 4, v65
	v_mad_u32_u24 v92, v66, s3, v152
	v_add_u32_e32 v66, s47, v66
	v_cmp_lt_i32_e32 vcc, -1, v66
	v_mov_b32_e32 v84, 0
	v_mov_b32_e32 v85, 0
	v_mov_b32_e32 v86, 0
	v_mov_b32_e32 v87, 0
	v_mov_b32_e32 v67, 0
	s_movk_i32 s44, 0xf0
	v_cmp_gt_u32_e64 s[44:45], s44, v10
	s_and_b64 vcc, vcc, s[44:45]
	s_and_saveexec_b64 s[44:45], vcc
	v_add_u32_e32 v66, s50, v66
	v_lshlrev_b64 v[66:67], 10, v[66:67]
	v_lshl_add_u64 v[66:67], v[12:13], 0, v[66:67]
	global_load_dwordx4 v[84:87], v[66:67], off
	s_or_b64 exec, exec, s[44:45]
	s_waitcnt vmcnt(0)
	ds_write_b128 v88, v[68:71]
	ds_write_b128 v89, v[72:75]
	ds_write_b128 v90, v[76:79]
	ds_write_b128 v91, v[80:83]
	v_cmp_gt_u32_e32 vcc, 0xf0, v10
	s_and_saveexec_b64 s[44:45], vcc
	ds_write_b128 v92, v[84:87]
	s_or_b64 exec, exec, s[44:45]
	s_branch .LBB0_448
	s_branch .LBB0_429
